# out-projection phase: workgroups with bit 3 of their index set run the thin sample-row GEMM before the main GEMM, the others after it
# baseline (speedup 1.0000x reference)
; #define TIDX opaque_tid()
; #define PG8_WAIT_V(n) asm volatile("s_waitcnt vmcnt(" #n ")" ::: "memory")
; template <class Epi>
; __device__ __forceinline__ void gemm_phase(LAS unsigned char* lds, const Gemm g, const StaticOrder& S, const Epi& E) {
;     const int tid = TIDX, wid = __builtin_amdgcn_readfirstlane(tid >> 6), lane = tid & 63, wr = wid >> 2, wc = wid & 3, fr = lane & 15, fq = lane >> 4;
;     const int K = g.K, nt = K / BK;
;     unsigned voffA[2], voffB[2];
; #pragma unroll
;     for (int i = 0; i < 2; ++i) { int R, C; stage_rc(tid * 16 + i * 8192, R, C); const int Rb = Epi::PERM ? ((R & ~31) + perm32(R & 31)) : R;
;         voffA[i] = (unsigned)(R * K + C) * 2u; voffB[i] = (unsigned)(Rb * K + C) * 2u; }
;     const size_t kstep = (size_t)(BK * 2);
;     const size_t hstep = (size_t)HALF * K * 2;
;     const size_t tstep = 2 * hstep;
;     const unsigned ldsw = (unsigned)wid * 1024u;
;     const int aoff = lds_byte(wr * 64 + fr, fq * 8), boff = lds_byte(wc * 32 + fr, fq * 8);
;     ...
;     Unit cur, nxt; int ui = 0;
;     if (!S.next(0, cur)) return;
;     f32x4 acc[2][2][4][2];
; #pragma unroll
;     for (int a = 0; a < 2; ++a)
; #pragma unroll
;         for (int b = 0; b < 2; ++b)
; #pragma unroll
;             for (int m = 0; m < 4; ++m)
; #pragma unroll
;                 for (int n = 0; n < 2; ++n) acc[a][b][m][n] = (f32x4){0.f, 0.f, 0.f, 0.f};
;     bf16x8 At[4][2], B0[2][2], B1[2][2];
;     const char* cA = (const char*)g.A + (size_t)cur.pm * tstep; const char* cB = (const char*)g.Bt + (size_t)cur.pn * tstep;
;     PG8_STAGE(PG8_SB(0, 0), cB, voffB); PG8_STAGE(PG8_SA(0, 0), cA, voffA); PG8_STAGE(PG8_SB(0, 1), cB + hstep, voffB); PG8_STAGE(PG8_SA(0, 1), cA + hstep, voffA);
;     if (wr == 1) PG8_BAR;
;     PG8_WAIT_V(4); PG8_BAR;
;     PG8_STAGE(PG8_SB(1, 0), cB + kstep, voffB); PG8_STAGE(PG8_SA(1, 0), cA + kstep, voffA); PG8_STAGE(PG8_SB(1, 1), cB + hstep + kstep, voffB);
; __device__ __forceinline__ void run_phase(const Params& p, LAS unsigned char* lds, int ph) {
;     ...
;         const bf16_t* W = (const bf16_t*)(p.ws + W_WOUT) + (size_t)l * DM * DMIX;
;         u64* r = rss + (size_t)(2 * l + 1) * TT;
;         S.init(TP, DM, gridDim.x, blockIdx.x);
;         pg8::gemm_phase(lds, pg8::Gemm{mix, W, TP, DM, DMIX}, S, pg8::EpiResid{DM, xb, r});
;         thin_gemm<DMIX, 1>(lds, mix + (size_t)TP * DMIX, W, DM, nullptr, DM, xb + (size_t)TP * DM, r + TP);
.Ls4_gemm_entry:
	v_readlane_b32 s2, v254, 48
	s_mul_hi_i32 s0, s2, 0x300000
	s_mul_i32 s1, s2, 0x300000
	v_readlane_b32 s2, v250, 11
	s_add_u32 s56, s2, s1
	v_readlane_b32 s1, v250, 12
	s_addc_u32 s57, s1, s0
	v_readlane_b32 s0, v251, 32
	s_nop 1
	s_cmp_lg_u32 s0, 0
	s_cbranch_scc1 .Ls4_gemm_go
	v_readlane_b32 s0, v250, 4
	s_nop 1
	s_bitcmp1_b32 s0, 6
	s_cbranch_scc0 .Ls4_gemm_go
	s_mov_b32 s0, 3
	v_writelane_b32 v251, s0, 32
	s_branch .LBB0_286
.Ls4_gemm_go:
	v_readlane_b32 s0, v250, 22
	v_mov_b32_e32 v10, v163
	v_readlane_b32 s1, v250, 23
	s_andn2_b64 vcc, exec, s[0:1]
	v_readfirstlane_b32 s30, v10
	v_readlane_b32 s3, v254, 49
	s_cbranch_vccnz .LBB0_286
	v_lshlrev_b32_e32 v0, 4, v10
	s_waitcnt lgkmcnt(0)
	v_add_u32_e32 v2, 0x2000, v0
	v_ashrrev_i32_e32 v3, 31, v2
	v_lshrrev_b32_e32 v3, 22, v3
	v_add_u32_e32 v3, v2, v3
	v_ashrrev_i32_e32 v6, 10, v3
	v_mul_i32_i24_e32 v3, 0x400, v6
	v_sub_u32_e32 v2, v2, v3
	v_lshrrev_b32_e32 v3, 4, v2
	v_bitop3_b32 v2, v3, v2, 32 bitop3:0x6c
	v_ashrrev_i32_e32 v3, 31, v2
	v_lshrrev_b32_e32 v3, 26, v3
	v_add_u32_e32 v3, v2, v3
	v_ashrrev_i32_e32 v7, 6, v3
	v_and_b32_e32 v3, 0xc0, v3
	v_sub_u32_e32 v2, v2, v3
	v_ashrrev_i16_sdwa v2, v228, sext(v2) dst_sel:DWORD dst_unused:UNUSED_PAD src0_sel:DWORD src1_sel:BYTE_0
	v_bfe_i32 v9, v2, 0, 16
	v_bfe_i32 v2, v10, 27, 1
	v_lshrrev_b32_e32 v2, 22, v2
	v_add_u32_e32 v2, v0, v2
	v_and_b32_e32 v2, 0xfffffc00, v2
	v_sub_u32_e32 v0, v0, v2
	v_lshrrev_b32_e32 v2, 4, v0
	v_bitop3_b32 v2, v2, v0, 32 bitop3:0x6c
	v_ashrrev_i32_e32 v0, 31, v0
	v_lshrrev_b32_e32 v0, 26, v0
	v_add_u32_e32 v0, v2, v0
	v_ashrrev_i32_e32 v11, 6, v0
	v_ashrrev_i32_e32 v0, 31, v10
	v_lshrrev_b32_e32 v0, 26, v0
	v_add_u32_e32 v0, v10, v0
	v_ashrrev_i32_e32 v12, 6, v0
	v_lshlrev_b32_e32 v4, 3, v6
	v_lshlrev_b32_e32 v0, 3, v12
	v_and_b32_e32 v4, 0x7ffff0, v4
	v_and_b32_e32 v0, 0x7ffff0, v0
	v_lshlrev_b32_e32 v3, 5, v12
	s_ashr_i32 s24, s30, 6
	v_add_u32_e32 v4, v7, v4
	s_movk_i32 s0, 0x600
	v_add_u32_e32 v0, v11, v0
	v_and_b32_e32 v13, 32, v3
	v_mul_i32_i24_e32 v3, 64, v11
	v_readlane_b32 s1, v252, 45
	s_ashr_i32 s26, s30, 8
	s_lshl_b32 s54, s24, 10
	v_mul_lo_u32 v4, v4, s0
	v_mul_lo_u32 v0, v0, s0
	v_sub_u32_e32 v2, v2, v3
	s_mul_i32 s0, s1, 0xc0000
	v_lshlrev_b32_e32 v5, 5, v6
	v_ashrrev_i16_sdwa v2, v228, sext(v2) dst_sel:DWORD dst_unused:UNUSED_PAD src0_sel:DWORD src1_sel:BYTE_0
	s_add_u32 s50, s56, s0
	s_mul_hi_i32 s0, s1, 0xc0000
	v_and_b32_e32 v8, 32, v5
	v_or_b32_e32 v0, v0, v13
	v_bfe_i32 v14, v2, 0, 16
	s_addc_u32 s51, s57, s0
	s_add_i32 s55, s54, 0
	v_or_b32_e32 v4, v4, v8
	v_add_lshl_u32 v0, v0, v14, 1
	s_add_i32 m0, s55, 0x10000
	v_add_lshl_u32 v130, v4, v9, 1
	global_load_lds_dwordx4 v0, s[50:51]
	s_add_i32 m0, s55, 0x12000
	v_readlane_b32 s0, v253, 2
	global_load_lds_dwordx4 v130, s[50:51]
	s_mov_b32 m0, s55
	v_readlane_b32 s1, v253, 3
	s_add_i32 s58, s55, 0x2000
	v_mov_b32_e32 v131, v1
	v_lshl_add_u64 v[2:3], s[50:51], 0, v[0:1]
	v_lshl_add_u64 v[4:5], s[50:51], 0, v[130:131]
	s_nop 0
	global_load_lds_dwordx4 v0, s[0:1]
	s_mov_b32 m0, s58
	s_nop 0
	global_load_lds_dwordx4 v130, s[0:1]
	s_add_u32 s0, s50, 0x60000
	s_addc_u32 s1, s51, 0
	s_add_i32 m0, s55, 0x14000
	s_add_i32 s59, s55, 0x4000
	global_load_lds_dwordx4 v0, s[0:1]
	s_add_i32 m0, s55, 0x16000
	s_add_i32 s61, s55, 0x6000
	global_load_lds_dwordx4 v130, s[0:1]
	v_readlane_b32 s0, v253, 4
	s_mov_b32 m0, s59
	v_readlane_b32 s1, v253, 5
	s_cmp_lg_u32 s26, 1
	s_nop 3
	global_load_lds_dwordx4 v0, s[0:1]
	s_mov_b32 m0, s61
	s_nop 0
	global_load_lds_dwordx4 v130, s[0:1]
	s_cbranch_scc1 .LBB0_246
	s_barrier

; __device__ __forceinline__ void run_phase(const Params& p, LAS unsigned char* lds, int ph) {
;     ...
;         pg8::gemm_phase(lds, pg8::Gemm{mix, W, TP, DM, DMIX}, S, pg8::EpiResid{DM, xb, r});
;         thin_gemm<DMIX, 1>(lds, mix + (size_t)TP * DMIX, W, DM, nullptr, DM, xb + (size_t)TP * DM, r + TP);
.LBB0_286:
	v_readlane_b32 s0, v251, 32
	s_nop 1
	s_cmp_eq_u32 s0, 4
	s_cbranch_scc0 .Ls4_thin_go
	s_mov_b32 s0, 0
	v_writelane_b32 v251, s0, 32
	s_branch .Ls4_295_cont

; __device__ __forceinline__ void run_phase(const Params& p, LAS unsigned char* lds, int ph) {
;     ...
;         pg8::gemm_phase(lds, pg8::Gemm{mix, W, TP, DM, DMIX}, S, pg8::EpiResid{DM, xb, r});
;         thin_gemm<DMIX, 1>(lds, mix + (size_t)TP * DMIX, W, DM, nullptr, DM, xb + (size_t)TP * DM, r + TP);
.LBB0_295:
	v_readlane_b32 s0, v251, 32
	s_nop 1
	s_cmp_eq_u32 s0, 3
	s_cbranch_scc0 .Ls4_295_cont
	s_mov_b32 s0, 4
	v_writelane_b32 v251, s0, 32
	s_branch .Ls4_gemm_entry
